# attention far tiles: second-half QK chain (3 MFMAs) deferred into PV gaps 1,3,5; head issues SA0-3,SB0 only
# baseline (speedup 1.0000x reference)
.LBB0_185:
	s_and_b64 vcc, exec, s[26:27]
	s_cbranch_vccz .LBB0_199
	s_lshl_b32 s22, s33, 14
	s_add_i32 s22, s22, 0
	s_nop 1
	s_add_i32 s100, s21, 64
	s_cmp_le_u32 s100, s20
	s_cbranch_scc1 .Lqk_far_u1e
	ds_read_b128 v[126:129], v249 offset:49152
	s_waitcnt lgkmcnt(1)
	v_mfma_f32_32x32x16_bf16 v[82:97], v[98:101], v[146:149], v[66:81]
	ds_read_b128 v[122:125], v102 offset:8192
	v_mfma_f32_32x32x16_bf16 v[98:113], v[114:117], v[146:149], v[66:81]
	v_add_u32_e32 v139, s22, v241
	ds_read_b128 v[114:117], v139
	v_mfma_f32_32x32x16_bf16 v[82:97], v[118:121], v[150:153], v[82:97]
	ds_read_b128 v[118:121], v139 offset:8192
	s_waitcnt lgkmcnt(0)
	v_mfma_f32_32x32x16_bf16 v[98:113], v[122:125], v[150:153], v[98:113]
	v_add_u32_e32 v139, s22, v243
	ds_read_b128 v[122:125], v139
	v_mfma_f32_32x32x16_bf16 v[82:97], v[114:117], v[154:157], v[82:97]
	ds_read_b128 v[114:117], v139 offset:8192
	v_mfma_f32_32x32x16_bf16 v[98:113], v[118:121], v[154:157], v[98:113]
	s_waitcnt lgkmcnt(0)
	v_mfma_f32_32x32x16_bf16 v[82:97], v[122:125], v[158:161], v[82:97]
	v_mfma_f32_32x32x16_bf16 v[98:113], v[114:117], v[158:161], v[98:113]
	s_nop 0
	ds_read_b128 v[122:125], v249 offset:53248
	ds_read_b128 v[118:121], v249 offset:57344
	ds_read_b128 v[114:117], v249 offset:61440
	s_add_i32 s22, s21, 64
	v_add_u32_e32 v130, s21, v248
	v_add_u32_e32 v130, 0x11f, v130
	v_and_b32_e32 v130, 0x3ffffffc, v130
	v_lshl_add_u32 v166, v130, 2, v0
	ds_read_b128 v[130:133], v166
	ds_read_b128 v[134:137], v166 offset:16
	ds_read_b128 v[138:141], v166 offset:64
	ds_read_b128 v[142:145], v166 offset:80
	s_waitcnt lgkmcnt(0)
	v_pk_add_f32 v[84:85], v[84:85], v[132:133]
	v_pk_add_f32 v[86:87], v[86:87], v[134:135]
	v_pk_add_f32 v[90:91], v[90:91], v[138:139]
	v_pk_add_f32 v[94:95], v[94:95], v[142:143]
	v_pk_add_f32 v[96:97], v[96:97], v[144:145]
	v_pk_add_f32 v[92:93], v[92:93], v[140:141]
	v_pk_add_f32 v[88:89], v[88:89], v[136:137]
	v_pk_add_f32 v[82:83], v[82:83], v[130:131]
	ds_read_b128 v[130:133], v166 offset:128
	ds_read_b128 v[134:137], v166 offset:144
	ds_read_b128 v[138:141], v166 offset:192
	ds_read_b128 v[142:145], v166 offset:208
	s_waitcnt lgkmcnt(0)
	v_pk_add_f32 v[100:101], v[100:101], v[132:133]
	v_pk_add_f32 v[102:103], v[102:103], v[134:135]
	v_pk_add_f32 v[106:107], v[106:107], v[138:139]
	v_pk_add_f32 v[110:111], v[110:111], v[142:143]
	v_pk_add_f32 v[112:113], v[112:113], v[144:145]
	v_pk_add_f32 v[108:109], v[108:109], v[140:141]
	v_pk_add_f32 v[104:105], v[104:105], v[136:137]
	v_pk_add_f32 v[98:99], v[98:99], v[130:131]
	v_mov_b32_e32 v194, 0
	v_mov_b32_e32 v195, 0
	v_mov_b32_e32 v196, 0
	v_mov_b32_e32 v197, 0
	v_mov_b32_e32 v198, 0
	v_mov_b32_e32 v199, 0
	v_mov_b32_e32 v200, 0
	v_mov_b32_e32 v201, 0
	v_mov_b32_e32 v202, 0
	v_mov_b32_e32 v203, 0
	v_mov_b32_e32 v204, 0
	v_mov_b32_e32 v205, 0
	s_branch .LBB0_188
.Lqk_far_u1e:
	v_add_u32_e32 v139, s22, v241
	ds_read_b128 v[122:125], v139
	v_add_u32_e32 v140, s22, v243
	ds_read_b128 v[206:209], v140
	ds_read_b128 v[126:129], v249 offset:49152
	ds_read_b128 v[194:197], v102 offset:8192
	ds_read_b128 v[198:201], v139 offset:8192
	ds_read_b128 v[202:205], v140 offset:8192
	s_waitcnt lgkmcnt(6)
	v_mfma_f32_32x32x16_bf16 v[82:97], v[98:101], v[146:149], v[66:81]
	v_mfma_f32_32x32x16_bf16 v[82:97], v[118:121], v[150:153], v[82:97]
	s_waitcnt lgkmcnt(5)
	v_mfma_f32_32x32x16_bf16 v[82:97], v[122:125], v[154:157], v[82:97]
	s_waitcnt lgkmcnt(4)
	v_mfma_f32_32x32x16_bf16 v[82:97], v[206:209], v[158:161], v[82:97]
	v_mfma_f32_32x32x16_bf16 v[98:113], v[114:117], v[146:149], v[66:81]
	ds_read_b128 v[122:125], v249 offset:53248
	ds_read_b128 v[118:121], v249 offset:57344
	ds_read_b128 v[114:117], v249 offset:61440
	s_add_i32 s22, s21, 64
.LBB0_188:
	s_waitcnt lgkmcnt(3)
	v_mfma_f32_32x32x16_bf16 v[34:49], v[126:129], v[162:165], v[34:49]
	ds_read_b128 v[126:129], v212 offset:49152
	s_nop 0
	v_exp_f32_e32 v130, v82
	v_exp_f32_e32 v131, v83
	v_add_f32_e32 v132, v1, v130
	v_add_f32_e32 v133, v1, v131
	v_cvt_pk_bf16_f32 v166, v130, v131
	s_waitcnt lgkmcnt(3)
	v_mfma_f32_32x32x16_bf16 v[50:65], v[122:125], v[162:165], v[50:65]
	ds_read_b128 v[122:125], v212 offset:53248
	v_exp_f32_e32 v134, v84
	v_exp_f32_e32 v135, v85
	v_mfma_f32_32x32x16_bf16 v[98:113], v[194:197], v[150:153], v[98:113]
	s_add_i32 s22, s23, 2
	s_cmp_lt_u32 s22, s17
	v_add_f32_e32 v130, v132, v134
	v_add_f32_e32 v131, v133, v135
	v_cvt_pk_bf16_f32 v167, v134, v135
	s_cselect_b64 s[26:27], -1, 0
	s_cmp_ge_u32 s22, s17
	s_cbranch_scc1 .LBB0_190
	s_lshl_b32 s40, s48, 14
	s_add_i32 m0, s11, s40
	s_add_u32 s100, s8, s80
	s_addc_u32 s101, s9, s81
	global_load_lds_dwordx4 v214, s[100:101]
.LBB0_190:
	s_waitcnt lgkmcnt(3)
	v_mfma_f32_32x32x16_bf16 v[18:33], v[118:121], v[162:165], v[18:33]
	ds_read_b128 v[118:121], v212 offset:57344
	v_exp_f32_e32 v132, v86
	v_exp_f32_e32 v133, v87
	v_add_f32_e32 v130, v130, v132
	v_add_f32_e32 v131, v131, v133
	v_cvt_pk_bf16_f32 v168, v132, v133
	s_waitcnt lgkmcnt(3)
	v_mfma_f32_32x32x16_bf16 v[2:17], v[114:117], v[162:165], v[2:17]
	ds_read_b128 v[114:117], v212 offset:61440
	v_exp_f32_e32 v132, v88
	v_exp_f32_e32 v133, v89
	v_mfma_f32_32x32x16_bf16 v[98:113], v[198:201], v[154:157], v[98:113]
	v_add_f32_e32 v134, v130, v132
	v_add_f32_e32 v131, v131, v133
	v_cvt_pk_bf16_f32 v169, v132, v133
	s_waitcnt lgkmcnt(3)
	v_mfma_f32_32x32x16_bf16 v[34:49], v[126:129], v[170:173], v[34:49]
	v_add_u32_e32 v130, s54, v246
	ds_read_b128 v[126:129], v130 offset:49152
	v_exp_f32_e32 v132, v90
	v_exp_f32_e32 v133, v91
	v_add_f32_e32 v134, v134, v132
	v_add_f32_e32 v135, v131, v133
	v_cvt_pk_bf16_f32 v174, v132, v133
	s_waitcnt lgkmcnt(3)
	v_mfma_f32_32x32x16_bf16 v[50:65], v[122:125], v[170:173], v[50:65]
	ds_read_b128 v[122:125], v130 offset:53248
	v_exp_f32_e32 v133, v92
	v_exp_f32_e32 v136, v93
	v_mfma_f32_32x32x16_bf16 v[98:113], v[202:205], v[158:161], v[98:113]
	v_add_f32_e32 v131, v134, v133
	v_add_f32_e32 v132, v135, v136
	s_andn2_b64 vcc, exec, s[26:27]
	v_cvt_pk_bf16_f32 v175, v133, v136
	s_cbranch_vccnz .LBB0_192
	s_lshl_b32 s26, s48, 14
	s_add_i32 s26, s11, s26
	s_add_i32 m0, s26, 0x2000
	s_add_u32 s100, s8, s62
	s_addc_u32 s101, s9, s63
	global_load_lds_dwordx4 v214, s[100:101]

.LBB0_225:
	s_and_b64 vcc, exec, s[26:27]
	s_cbranch_vccz .LBB0_239
	s_lshl_b32 s26, s33, 14
	s_add_i32 s26, s26, 0
	s_nop 1
	s_add_i32 s100, s21, 0x80
	s_cmp_le_u32 s100, s20
	s_cbranch_scc1 .Lqk_far_u1o
	ds_read_b128 v[126:129], v249 offset:49152
	s_waitcnt lgkmcnt(1)
	v_mfma_f32_32x32x16_bf16 v[82:97], v[98:101], v[146:149], v[66:81]
	ds_read_b128 v[122:125], v102 offset:8192
	v_mfma_f32_32x32x16_bf16 v[98:113], v[114:117], v[146:149], v[66:81]
	v_add_u32_e32 v139, s26, v241
	ds_read_b128 v[114:117], v139
	v_mfma_f32_32x32x16_bf16 v[82:97], v[118:121], v[150:153], v[82:97]
	ds_read_b128 v[118:121], v139 offset:8192
	s_waitcnt lgkmcnt(0)
	v_mfma_f32_32x32x16_bf16 v[98:113], v[122:125], v[150:153], v[98:113]
	v_add_u32_e32 v139, s26, v243
	ds_read_b128 v[122:125], v139
	v_mfma_f32_32x32x16_bf16 v[82:97], v[114:117], v[154:157], v[82:97]
	ds_read_b128 v[114:117], v139 offset:8192
	v_mfma_f32_32x32x16_bf16 v[98:113], v[118:121], v[154:157], v[98:113]
	s_waitcnt lgkmcnt(0)
	v_mfma_f32_32x32x16_bf16 v[82:97], v[122:125], v[158:161], v[82:97]
	v_mfma_f32_32x32x16_bf16 v[98:113], v[114:117], v[158:161], v[98:113]
	s_nop 0
	ds_read_b128 v[122:125], v249 offset:53248
	ds_read_b128 v[118:121], v249 offset:57344
	ds_read_b128 v[114:117], v249 offset:61440
	s_add_i32 s26, s21, 0x80
	v_add_u32_e32 v130, s21, v248
	v_add_u32_e32 v130, 0x15f, v130
	v_and_b32_e32 v130, 0x3ffffffc, v130
	v_lshl_add_u32 v162, v130, 2, v0
	ds_read_b128 v[130:133], v162
	ds_read_b128 v[134:137], v162 offset:16
	ds_read_b128 v[138:141], v162 offset:64
	ds_read_b128 v[142:145], v162 offset:80
	s_waitcnt lgkmcnt(0)
	v_pk_add_f32 v[84:85], v[84:85], v[132:133]
	v_pk_add_f32 v[86:87], v[86:87], v[134:135]
	v_pk_add_f32 v[90:91], v[90:91], v[138:139]
	v_pk_add_f32 v[94:95], v[94:95], v[142:143]
	v_pk_add_f32 v[96:97], v[96:97], v[144:145]
	v_pk_add_f32 v[92:93], v[92:93], v[140:141]
	v_pk_add_f32 v[88:89], v[88:89], v[136:137]
	v_pk_add_f32 v[82:83], v[82:83], v[130:131]
	ds_read_b128 v[130:133], v162 offset:128
	ds_read_b128 v[134:137], v162 offset:144
	ds_read_b128 v[138:141], v162 offset:192
	ds_read_b128 v[142:145], v162 offset:208
	s_waitcnt lgkmcnt(0)
	v_pk_add_f32 v[100:101], v[100:101], v[132:133]
	v_pk_add_f32 v[102:103], v[102:103], v[134:135]
	v_pk_add_f32 v[106:107], v[106:107], v[138:139]
	v_pk_add_f32 v[110:111], v[110:111], v[142:143]
	v_pk_add_f32 v[112:113], v[112:113], v[144:145]
	v_pk_add_f32 v[108:109], v[108:109], v[140:141]
	v_pk_add_f32 v[104:105], v[104:105], v[136:137]
	v_pk_add_f32 v[98:99], v[98:99], v[130:131]
	v_mov_b32_e32 v194, 0
	v_mov_b32_e32 v195, 0
	v_mov_b32_e32 v196, 0
	v_mov_b32_e32 v197, 0
	v_mov_b32_e32 v198, 0
	v_mov_b32_e32 v199, 0
	v_mov_b32_e32 v200, 0
	v_mov_b32_e32 v201, 0
	v_mov_b32_e32 v202, 0
	v_mov_b32_e32 v203, 0
	v_mov_b32_e32 v204, 0
	v_mov_b32_e32 v205, 0
	s_branch .LBB0_228
.Lqk_far_u1o:
	v_add_u32_e32 v139, s26, v241
	ds_read_b128 v[122:125], v139
	v_add_u32_e32 v140, s26, v243
	ds_read_b128 v[206:209], v140
	ds_read_b128 v[126:129], v249 offset:49152
	ds_read_b128 v[194:197], v102 offset:8192
	ds_read_b128 v[198:201], v139 offset:8192
	ds_read_b128 v[202:205], v140 offset:8192
	s_waitcnt lgkmcnt(6)
	v_mfma_f32_32x32x16_bf16 v[82:97], v[98:101], v[146:149], v[66:81]
	v_mfma_f32_32x32x16_bf16 v[82:97], v[118:121], v[150:153], v[82:97]
	s_waitcnt lgkmcnt(5)
	v_mfma_f32_32x32x16_bf16 v[82:97], v[122:125], v[154:157], v[82:97]
	s_waitcnt lgkmcnt(4)
	v_mfma_f32_32x32x16_bf16 v[82:97], v[206:209], v[158:161], v[82:97]
	v_mfma_f32_32x32x16_bf16 v[98:113], v[114:117], v[146:149], v[66:81]
	ds_read_b128 v[122:125], v249 offset:53248
	ds_read_b128 v[118:121], v249 offset:57344
	ds_read_b128 v[114:117], v249 offset:61440
	s_add_i32 s26, s21, 0x80
.LBB0_228:
	s_waitcnt lgkmcnt(3)
	v_mfma_f32_32x32x16_bf16 v[34:49], v[126:129], v[166:169], v[34:49]
	ds_read_b128 v[126:129], v212 offset:49152
	s_nop 0
	v_exp_f32_e32 v130, v82
	v_exp_f32_e32 v131, v83
	v_add_f32_e32 v132, v1, v130
	v_add_f32_e32 v133, v1, v131
	v_cvt_pk_bf16_f32 v162, v130, v131
	s_waitcnt lgkmcnt(3)
	v_mfma_f32_32x32x16_bf16 v[50:65], v[122:125], v[166:169], v[50:65]
	ds_read_b128 v[122:125], v212 offset:53248
	v_exp_f32_e32 v130, v84
	v_exp_f32_e32 v131, v85
	v_mfma_f32_32x32x16_bf16 v[98:113], v[194:197], v[150:153], v[98:113]
	s_add_i32 s23, s23, 3
	s_cmp_le_u32 s23, s16
	v_add_f32_e32 v132, v132, v130
	v_add_f32_e32 v133, v133, v131
	v_cvt_pk_bf16_f32 v163, v130, v131
	s_cselect_b64 s[26:27], -1, 0
	s_cmp_gt_u32 s23, s16
	v_lshl_add_u64 v[130:131], s[8:9], 0, v[214:215]
	s_cbranch_scc1 .LBB0_230
	s_lshl_b32 s23, s48, 14
	v_lshl_add_u64 v[134:135], v[130:131], 0, s[50:51]
	s_add_i32 m0, s11, s23
	s_nop 0
	global_load_lds_dwordx4 v[134:135], off
.LBB0_230:
	s_waitcnt lgkmcnt(3)
	v_mfma_f32_32x32x16_bf16 v[18:33], v[118:121], v[166:169], v[18:33]
	ds_read_b128 v[118:121], v212 offset:57344
	v_exp_f32_e32 v134, v86
	v_exp_f32_e32 v135, v87
	v_add_f32_e32 v132, v132, v134
	v_add_f32_e32 v133, v133, v135
	v_cvt_pk_bf16_f32 v164, v134, v135
	s_waitcnt lgkmcnt(3)
	v_mfma_f32_32x32x16_bf16 v[2:17], v[114:117], v[166:169], v[2:17]
	ds_read_b128 v[114:117], v212 offset:61440
	v_exp_f32_e32 v134, v88
	v_exp_f32_e32 v135, v89
	v_mfma_f32_32x32x16_bf16 v[98:113], v[198:201], v[154:157], v[98:113]
	v_add_f32_e32 v136, v132, v134
	v_add_f32_e32 v133, v133, v135
	v_cvt_pk_bf16_f32 v165, v134, v135
	s_waitcnt lgkmcnt(3)
	v_mfma_f32_32x32x16_bf16 v[34:49], v[126:129], v[174:177], v[34:49]
	v_add_u32_e32 v132, s54, v246
	ds_read_b128 v[126:129], v132 offset:49152
	v_exp_f32_e32 v134, v90
	v_exp_f32_e32 v135, v91
	v_add_f32_e32 v136, v136, v134
	v_add_f32_e32 v137, v133, v135
	v_cvt_pk_bf16_f32 v170, v134, v135
	s_waitcnt lgkmcnt(3)
	v_mfma_f32_32x32x16_bf16 v[50:65], v[122:125], v[174:177], v[50:65]
	ds_read_b128 v[122:125], v132 offset:53248
	v_exp_f32_e32 v135, v92
	v_exp_f32_e32 v138, v93
	v_mfma_f32_32x32x16_bf16 v[98:113], v[202:205], v[158:161], v[98:113]
	v_add_f32_e32 v133, v136, v135
	v_add_f32_e32 v134, v137, v138
	s_andn2_b64 vcc, exec, s[26:27]
	v_cvt_pk_bf16_f32 v171, v135, v138
	s_cbranch_vccnz .LBB0_232
	s_lshl_b32 s23, s48, 14
	s_add_i32 s23, s11, s23
	v_lshl_add_u64 v[130:131], v[130:131], 0, s[4:5]
	s_add_i32 m0, s23, 0x2000
	s_nop 0
	global_load_lds_dwordx4 v[130:131], off

.LBB0_288:
	s_and_b64 vcc, exec, s[26:27]
	s_cbranch_vccz .LBB0_302
	s_lshl_b32 s21, s31, 14
	s_add_i32 s21, s21, 0
	s_nop 1
	s_cmp_le_u32 s20, s16
	s_cbranch_scc1 .Lqk_far_u2e
	ds_read_b128 v[126:129], v212 offset:49152
	s_waitcnt lgkmcnt(1)
	v_mfma_f32_32x32x16_bf16 v[82:97], v[98:101], v[146:149], v[66:81]
	ds_read_b128 v[122:125], v102 offset:8192
	v_mfma_f32_32x32x16_bf16 v[98:113], v[114:117], v[146:149], v[66:81]
	v_add_u32_e32 v139, s21, v241
	ds_read_b128 v[114:117], v139
	v_mfma_f32_32x32x16_bf16 v[82:97], v[118:121], v[150:153], v[82:97]
	ds_read_b128 v[118:121], v139 offset:8192
	s_waitcnt lgkmcnt(0)
	v_mfma_f32_32x32x16_bf16 v[98:113], v[122:125], v[150:153], v[98:113]
	v_add_u32_e32 v139, s21, v242
	ds_read_b128 v[122:125], v139
	v_mfma_f32_32x32x16_bf16 v[82:97], v[114:117], v[154:157], v[82:97]
	ds_read_b128 v[114:117], v139 offset:8192
	v_mfma_f32_32x32x16_bf16 v[98:113], v[118:121], v[154:157], v[98:113]
	s_waitcnt lgkmcnt(0)
	v_mfma_f32_32x32x16_bf16 v[82:97], v[122:125], v[158:161], v[82:97]
	v_mfma_f32_32x32x16_bf16 v[98:113], v[114:117], v[158:161], v[98:113]
	s_nop 0
	ds_read_b128 v[122:125], v212 offset:53248
	ds_read_b128 v[118:121], v212 offset:57344
	ds_read_b128 v[114:117], v212 offset:61440
	v_add3_u32 v130, v249, s20, 47
	v_and_b32_e32 v130, 0x3ffffffc, v130
	v_lshl_add_u32 v166, v130, 2, v244
	ds_read_b128 v[130:133], v166
	ds_read_b128 v[134:137], v166 offset:16
	ds_read_b128 v[138:141], v166 offset:64
	ds_read_b128 v[142:145], v166 offset:80
	s_waitcnt lgkmcnt(0)
	v_pk_add_f32 v[84:85], v[84:85], v[132:133]
	v_pk_add_f32 v[88:89], v[88:89], v[136:137]
	v_pk_add_f32 v[92:93], v[92:93], v[140:141]
	v_pk_add_f32 v[96:97], v[96:97], v[144:145]
	v_pk_add_f32 v[94:95], v[94:95], v[142:143]
	v_pk_add_f32 v[90:91], v[90:91], v[138:139]
	v_pk_add_f32 v[86:87], v[86:87], v[134:135]
	v_pk_add_f32 v[82:83], v[82:83], v[130:131]
	ds_read_b128 v[130:133], v166 offset:128
	ds_read_b128 v[134:137], v166 offset:144
	ds_read_b128 v[138:141], v166 offset:192
	ds_read_b128 v[142:145], v166 offset:208
	s_waitcnt lgkmcnt(0)
	v_pk_add_f32 v[100:101], v[100:101], v[132:133]
	v_pk_add_f32 v[104:105], v[104:105], v[136:137]
	v_pk_add_f32 v[108:109], v[108:109], v[140:141]
	v_pk_add_f32 v[112:113], v[112:113], v[144:145]
	v_pk_add_f32 v[110:111], v[110:111], v[142:143]
	v_pk_add_f32 v[106:107], v[106:107], v[138:139]
	v_pk_add_f32 v[102:103], v[102:103], v[134:135]
	v_pk_add_f32 v[98:99], v[98:99], v[130:131]
	v_mov_b32_e32 v194, 0
	v_mov_b32_e32 v195, 0
	v_mov_b32_e32 v196, 0
	v_mov_b32_e32 v197, 0
	v_mov_b32_e32 v198, 0
	v_mov_b32_e32 v199, 0
	v_mov_b32_e32 v200, 0
	v_mov_b32_e32 v201, 0
	v_mov_b32_e32 v202, 0
	v_mov_b32_e32 v203, 0
	v_mov_b32_e32 v204, 0
	v_mov_b32_e32 v205, 0
	s_branch .LBB0_291
.Lqk_far_u2e:
	v_add_u32_e32 v139, s21, v241
	ds_read_b128 v[122:125], v139
	v_add_u32_e32 v140, s21, v242
	ds_read_b128 v[206:209], v140
	ds_read_b128 v[126:129], v212 offset:49152
	ds_read_b128 v[194:197], v102 offset:8192
	ds_read_b128 v[198:201], v139 offset:8192
	ds_read_b128 v[202:205], v140 offset:8192
	s_waitcnt lgkmcnt(6)
	v_mfma_f32_32x32x16_bf16 v[82:97], v[98:101], v[146:149], v[66:81]
	v_mfma_f32_32x32x16_bf16 v[82:97], v[118:121], v[150:153], v[82:97]
	s_waitcnt lgkmcnt(5)
	v_mfma_f32_32x32x16_bf16 v[82:97], v[122:125], v[154:157], v[82:97]
	s_waitcnt lgkmcnt(4)
	v_mfma_f32_32x32x16_bf16 v[82:97], v[206:209], v[158:161], v[82:97]
	v_mfma_f32_32x32x16_bf16 v[98:113], v[114:117], v[146:149], v[66:81]
	ds_read_b128 v[122:125], v212 offset:53248
	ds_read_b128 v[118:121], v212 offset:57344
	ds_read_b128 v[114:117], v212 offset:61440
.LBB0_291:
	s_waitcnt lgkmcnt(3)
	v_mfma_f32_32x32x16_bf16 v[50:65], v[126:129], v[162:165], v[50:65]
	ds_read_b128 v[126:129], v0 offset:49152
	s_nop 1
	v_exp_f32_e32 v130, v82
	v_exp_f32_e32 v131, v83
	v_add_f32_e32 v132, v1, v130
	v_add_f32_e32 v133, v1, v131
	v_cvt_pk_bf16_f32 v166, v130, v131
	s_waitcnt lgkmcnt(3)
	v_mfma_f32_32x32x16_bf16 v[34:49], v[122:125], v[162:165], v[34:49]
	ds_read_b128 v[122:125], v0 offset:53248
	v_exp_f32_e32 v134, v84
	v_exp_f32_e32 v135, v85
	v_mfma_f32_32x32x16_bf16 v[98:113], v[194:197], v[150:153], v[98:113]
	s_add_i32 s21, s22, 2
	s_cmp_lt_u32 s21, s18
	v_add_f32_e32 v130, v132, v134
	v_add_f32_e32 v131, v133, v135
	v_cvt_pk_bf16_f32 v167, v134, v135
	s_cselect_b64 s[26:27], -1, 0
	s_cmp_ge_u32 s21, s18
	s_cbranch_scc1 .LBB0_293
	s_lshl_b32 s37, s28, 14
	s_add_i32 m0, s10, s37
	s_add_u32 s100, s8, s80
	s_addc_u32 s101, s9, s81
	global_load_lds_dwordx4 v214, s[100:101]
.LBB0_293:
	s_waitcnt lgkmcnt(3)
	v_mfma_f32_32x32x16_bf16 v[18:33], v[118:121], v[162:165], v[18:33]
	ds_read_b128 v[118:121], v0 offset:57344
	v_exp_f32_e32 v132, v86
	v_exp_f32_e32 v133, v87
	v_add_f32_e32 v130, v130, v132
	v_add_f32_e32 v131, v131, v133
	v_cvt_pk_bf16_f32 v168, v132, v133
	s_waitcnt lgkmcnt(3)
	v_mfma_f32_32x32x16_bf16 v[2:17], v[114:117], v[162:165], v[2:17]
	ds_read_b128 v[114:117], v0 offset:61440
	v_exp_f32_e32 v0, v88
	v_exp_f32_e32 v132, v89
	v_mfma_f32_32x32x16_bf16 v[98:113], v[198:201], v[154:157], v[98:113]
	v_add_f32_e32 v130, v130, v0
	v_add_f32_e32 v131, v131, v132
	v_cvt_pk_bf16_f32 v169, v0, v132
	s_waitcnt lgkmcnt(3)
	v_mfma_f32_32x32x16_bf16 v[50:65], v[126:129], v[170:173], v[50:65]
	v_add_u32_e32 v0, s36, v247
	ds_read_b128 v[126:129], v0 offset:49152
	v_exp_f32_e32 v132, v90
	v_exp_f32_e32 v133, v91
	v_add_f32_e32 v130, v130, v132
	v_add_f32_e32 v131, v131, v133
	v_cvt_pk_bf16_f32 v174, v132, v133
	s_waitcnt lgkmcnt(3)
	v_mfma_f32_32x32x16_bf16 v[34:49], v[122:125], v[170:173], v[34:49]
	ds_read_b128 v[122:125], v0 offset:53248
	v_exp_f32_e32 v132, v92
	v_exp_f32_e32 v133, v93
	v_mfma_f32_32x32x16_bf16 v[98:113], v[202:205], v[158:161], v[98:113]
	v_add_f32_e32 v130, v130, v132
	v_add_f32_e32 v131, v131, v133
	s_andn2_b64 vcc, exec, s[26:27]
	v_cvt_pk_bf16_f32 v175, v132, v133
	s_cbranch_vccnz .LBB0_295
	s_lshl_b32 s26, s28, 14
	s_add_i32 s26, s10, s26
	s_add_i32 m0, s26, 0x2000
	s_add_u32 s100, s8, s62
	s_addc_u32 s101, s9, s63
	global_load_lds_dwordx4 v214, s[100:101]

.LBB0_328:
	s_and_b64 vcc, exec, s[26:27]
	s_cbranch_vccz .LBB0_342
	s_lshl_b32 s26, s31, 14
	s_add_i32 s26, s26, 0
	s_nop 1
	s_add_i32 s100, s20, 64
	s_cmp_le_u32 s100, s16
	s_cbranch_scc1 .Lqk_far_u2o
	ds_read_b128 v[126:129], v212 offset:49152
	s_waitcnt lgkmcnt(1)
	v_mfma_f32_32x32x16_bf16 v[82:97], v[98:101], v[146:149], v[66:81]
	ds_read_b128 v[122:125], v102 offset:8192
	v_mfma_f32_32x32x16_bf16 v[98:113], v[114:117], v[146:149], v[66:81]
	v_add_u32_e32 v139, s26, v241
	ds_read_b128 v[114:117], v139
	v_mfma_f32_32x32x16_bf16 v[82:97], v[118:121], v[150:153], v[82:97]
	ds_read_b128 v[118:121], v139 offset:8192
	s_waitcnt lgkmcnt(0)
	v_mfma_f32_32x32x16_bf16 v[98:113], v[122:125], v[150:153], v[98:113]
	v_add_u32_e32 v139, s26, v242
	ds_read_b128 v[122:125], v139
	v_mfma_f32_32x32x16_bf16 v[82:97], v[114:117], v[154:157], v[82:97]
	ds_read_b128 v[114:117], v139 offset:8192
	v_mfma_f32_32x32x16_bf16 v[98:113], v[118:121], v[154:157], v[98:113]
	s_waitcnt lgkmcnt(0)
	v_mfma_f32_32x32x16_bf16 v[82:97], v[122:125], v[158:161], v[82:97]
	v_mfma_f32_32x32x16_bf16 v[98:113], v[114:117], v[158:161], v[98:113]
	s_nop 0
	ds_read_b128 v[122:125], v212 offset:53248
	ds_read_b128 v[118:121], v212 offset:57344
	ds_read_b128 v[114:117], v212 offset:61440
	s_add_i32 s26, s20, 64
	v_add_u32_e32 v130, s20, v249
	v_add_u32_e32 v130, 0x6f, v130
	v_and_b32_e32 v130, 0x3ffffffc, v130
	v_lshl_add_u32 v162, v130, 2, v244
	ds_read_b128 v[130:133], v162
	ds_read_b128 v[134:137], v162 offset:16
	ds_read_b128 v[138:141], v162 offset:64
	ds_read_b128 v[142:145], v162 offset:80
	s_waitcnt lgkmcnt(0)
	v_pk_add_f32 v[84:85], v[84:85], v[132:133]
	v_pk_add_f32 v[86:87], v[86:87], v[134:135]
	v_pk_add_f32 v[90:91], v[90:91], v[138:139]
	v_pk_add_f32 v[94:95], v[94:95], v[142:143]
	v_pk_add_f32 v[96:97], v[96:97], v[144:145]
	v_pk_add_f32 v[92:93], v[92:93], v[140:141]
	v_pk_add_f32 v[88:89], v[88:89], v[136:137]
	v_pk_add_f32 v[82:83], v[82:83], v[130:131]
	ds_read_b128 v[130:133], v162 offset:128
	ds_read_b128 v[134:137], v162 offset:144
	ds_read_b128 v[138:141], v162 offset:192
	ds_read_b128 v[142:145], v162 offset:208
	s_waitcnt lgkmcnt(0)
	v_pk_add_f32 v[100:101], v[100:101], v[132:133]
	v_pk_add_f32 v[102:103], v[102:103], v[134:135]
	v_pk_add_f32 v[106:107], v[106:107], v[138:139]
	v_pk_add_f32 v[110:111], v[110:111], v[142:143]
	v_pk_add_f32 v[112:113], v[112:113], v[144:145]
	v_pk_add_f32 v[108:109], v[108:109], v[140:141]
	v_pk_add_f32 v[104:105], v[104:105], v[136:137]
	v_pk_add_f32 v[98:99], v[98:99], v[130:131]
	v_mov_b32_e32 v194, 0
	v_mov_b32_e32 v195, 0
	v_mov_b32_e32 v196, 0
	v_mov_b32_e32 v197, 0
	v_mov_b32_e32 v198, 0
	v_mov_b32_e32 v199, 0
	v_mov_b32_e32 v200, 0
	v_mov_b32_e32 v201, 0
	v_mov_b32_e32 v202, 0
	v_mov_b32_e32 v203, 0
	v_mov_b32_e32 v204, 0
	v_mov_b32_e32 v205, 0
	s_branch .LBB0_331
.Lqk_far_u2o:
	v_add_u32_e32 v139, s26, v241
	ds_read_b128 v[122:125], v139
	v_add_u32_e32 v140, s26, v242
	ds_read_b128 v[206:209], v140
	ds_read_b128 v[126:129], v212 offset:49152
	ds_read_b128 v[194:197], v102 offset:8192
	ds_read_b128 v[198:201], v139 offset:8192
	ds_read_b128 v[202:205], v140 offset:8192
	s_waitcnt lgkmcnt(6)
	v_mfma_f32_32x32x16_bf16 v[82:97], v[98:101], v[146:149], v[66:81]
	v_mfma_f32_32x32x16_bf16 v[82:97], v[118:121], v[150:153], v[82:97]
	s_waitcnt lgkmcnt(5)
	v_mfma_f32_32x32x16_bf16 v[82:97], v[122:125], v[154:157], v[82:97]
	s_waitcnt lgkmcnt(4)
	v_mfma_f32_32x32x16_bf16 v[82:97], v[206:209], v[158:161], v[82:97]
	v_mfma_f32_32x32x16_bf16 v[98:113], v[114:117], v[146:149], v[66:81]
	ds_read_b128 v[122:125], v212 offset:53248
	ds_read_b128 v[118:121], v212 offset:57344
	ds_read_b128 v[114:117], v212 offset:61440
	s_add_i32 s26, s20, 64
.LBB0_331:
	s_waitcnt lgkmcnt(3)
	v_mfma_f32_32x32x16_bf16 v[50:65], v[126:129], v[166:169], v[50:65]
	ds_read_b128 v[126:129], v0 offset:49152
	s_nop 0
	v_exp_f32_e32 v130, v82
	v_exp_f32_e32 v131, v83
	v_add_f32_e32 v132, v1, v130
	v_add_f32_e32 v133, v1, v131
	v_cvt_pk_bf16_f32 v162, v130, v131
	s_waitcnt lgkmcnt(3)
	v_mfma_f32_32x32x16_bf16 v[34:49], v[122:125], v[166:169], v[34:49]
	ds_read_b128 v[122:125], v0 offset:53248
	v_exp_f32_e32 v130, v84
	v_exp_f32_e32 v131, v85
	v_mfma_f32_32x32x16_bf16 v[98:113], v[194:197], v[150:153], v[98:113]
	s_add_i32 s22, s22, 3
	s_cmp_le_u32 s22, s17
	v_add_f32_e32 v132, v132, v130
	v_add_f32_e32 v133, v133, v131
	v_cvt_pk_bf16_f32 v163, v130, v131
	s_cselect_b64 s[26:27], -1, 0
	s_cmp_gt_u32 s22, s17
	v_lshl_add_u64 v[130:131], s[8:9], 0, v[214:215]
	s_cbranch_scc1 .LBB0_333
	s_lshl_b32 s22, s28, 14
	v_lshl_add_u64 v[134:135], v[130:131], 0, s[50:51]
	s_add_i32 m0, s10, s22
	s_nop 0
	global_load_lds_dwordx4 v[134:135], off
.LBB0_333:
	s_waitcnt lgkmcnt(3)
	v_mfma_f32_32x32x16_bf16 v[18:33], v[118:121], v[166:169], v[18:33]
	ds_read_b128 v[118:121], v0 offset:57344
	v_exp_f32_e32 v134, v86
	v_exp_f32_e32 v135, v87
	v_add_f32_e32 v132, v132, v134
	v_add_f32_e32 v133, v133, v135
	v_cvt_pk_bf16_f32 v164, v134, v135
	s_waitcnt lgkmcnt(3)
	v_mfma_f32_32x32x16_bf16 v[2:17], v[114:117], v[166:169], v[2:17]
	ds_read_b128 v[114:117], v0 offset:61440
	v_exp_f32_e32 v0, v88
	v_exp_f32_e32 v134, v89
	v_mfma_f32_32x32x16_bf16 v[98:113], v[198:201], v[154:157], v[98:113]
	v_add_f32_e32 v132, v132, v0
	v_add_f32_e32 v133, v133, v134
	v_cvt_pk_bf16_f32 v165, v0, v134
	s_waitcnt lgkmcnt(3)
	v_mfma_f32_32x32x16_bf16 v[50:65], v[126:129], v[174:177], v[50:65]
	v_add_u32_e32 v0, s36, v247
	ds_read_b128 v[126:129], v0 offset:49152
	v_exp_f32_e32 v134, v90
	v_exp_f32_e32 v135, v91
	v_add_f32_e32 v132, v132, v134
	v_add_f32_e32 v133, v133, v135
	v_cvt_pk_bf16_f32 v170, v134, v135
	s_waitcnt lgkmcnt(3)
	v_mfma_f32_32x32x16_bf16 v[34:49], v[122:125], v[174:177], v[34:49]
	ds_read_b128 v[122:125], v0 offset:53248
	v_exp_f32_e32 v134, v92
	v_exp_f32_e32 v135, v93
	v_mfma_f32_32x32x16_bf16 v[98:113], v[202:205], v[158:161], v[98:113]
	v_add_f32_e32 v132, v132, v134
	v_add_f32_e32 v133, v133, v135
	s_andn2_b64 vcc, exec, s[26:27]
	v_cvt_pk_bf16_f32 v171, v134, v135
	s_cbranch_vccnz .LBB0_335
	s_lshl_b32 s22, s28, 14
	s_add_i32 s22, s10, s22
	v_lshl_add_u64 v[130:131], v[130:131], 0, s[4:5]
	s_add_i32 m0, s22, 0x2000
	s_nop 0
	global_load_lds_dwordx4 v[130:131], off
